# LRU: tile 0 conv-window loads prefetched in the unit prologue; tile loop always consumes prefetched registers (run 1)
# baseline (speedup 1.0000x reference)
; __device__ __forceinline__ float bf2f(bf16 b) { return __uint_as_float((unsigned)b << 16); }
;     __device__ __forceinline__ int nt(const Unit& u, int) const { return (u.pn >> 2) == 0 ? 4 : 8; }
; __device__ __forceinline__ void lru_unit(const Ctx& C, const Params& p, int l, int unit) {
;     ...
;     const float* cwp = p.in[4] + (size_t)l * 4 * 512;
;     const float cw0 = cwp[ch], cw1 = cwp[512 + ch], cw2 = cwp[1024 + ch], cw3 = cwp[1536 + ch];
;     const float cb = p.in[5][l * 512 + ch], ba = p.in[7][l * 512 + ch], bx = p.in[9][l * 512 + ch];
;     const float lam = p.in[10][l * 512 + ch];
;     const float logu = -8.0f * log1pf(expf(-lam));
;     const bf16* WaT = (const bf16*)wla_ptr(C.ws, l) + nb * 4096;
;     const bf16* WxT = (const bf16*)wlx_ptr(C.ws, l) + nb * 4096;
;     bf16x8 wa[4][2], wx[4][2];
; #pragma unroll
;     for (int nt = 0; nt < 4; ++nt)
; #pragma unroll
;         for (int ks = 0; ks < 2; ++ks) { wa[nt][ks] = *(const bf16x8*)(WaT + (16 * nt + i16) * 64 + 32 * ks + 8 * g); wx[nt][ks] = *(const bf16x8*)(WxT + (16 * nt + i16) * 64 + 32 * ks + 8 * g); }
;     if (tid < 64) { CAR[tid] = 0.f; CARP[tid] = 1.f; }
;     __syncthreads();
; #pragma unroll 1
;     for (int tile = 0; tile < 2; ++tile) {
;         const int tl0 = tile * 128 + 16 * tg, t0 = tc * 256 + tl0;
;         float xw[19], gbv[16], xc[16];
; #pragma unroll
;         for (int k = 0; k < 19; ++k) { const int t = t0 - 3 + k; xw[k] = (t >= 0) ? bf2f(Zb[(size_t)t * ZC + XB + ch]) : 0.f; }
.Llru_pf1_skip:
	s_and_b32 s21, s74, 7
	s_lshl_b32 s56, s21, 6
	v_or_b32_e32 v114, s56, v169
	s_lshl_b32 s22, s20, 9
	v_lshlrev_b32_e32 v192, 2, v114
	v_readlane_b32 s0, v247, 13
	s_and_b32 s57, s22, 0x7000
	v_lshl_add_u64 v[0:1], s[60:61], 0, v[192:193]
	global_load_dword v115, v192, s[60:61]
	global_load_dword v116, v192, s[60:61] offset:2048
	v_or_b32_e32 v192, s0, v114
	v_readlane_b32 s0, v247, 10
	s_add_u32 s22, s64, s0
	s_addc_u32 s23, s65, 0
	s_lshl_b32 s21, s21, 13
	s_add_u32 s22, s22, s21
	v_add_co_u32_e32 v0, vcc, 0x1000, v0
	s_addc_u32 s23, s23, 0
	v_readlane_b32 s0, v247, 16
	v_addc_co_u32_e32 v1, vcc, 0, v1, vcc
	v_readlane_b32 s40, v249, 42
	s_add_u32 s24, s64, s0
	global_load_dword v117, v[0:1], off
	global_load_dword v118, v[0:1], off offset:2048
	v_lshlrev_b64 v[0:1], 2, v[192:193]
	v_readlane_b32 s50, v249, 52
	v_readlane_b32 s51, v249, 53
	s_addc_u32 s25, s65, 0
	v_readlane_b32 s41, v249, 43
	v_readlane_b32 s42, v249, 44
	v_readlane_b32 s43, v249, 45
	v_readlane_b32 s44, v249, 46
	v_readlane_b32 s45, v249, 47
	v_readlane_b32 s46, v249, 48
	v_readlane_b32 s47, v249, 49
	v_readlane_b32 s48, v249, 50
	v_readlane_b32 s49, v249, 51
	v_readlane_b32 s52, v249, 54
	v_readlane_b32 s53, v249, 55
	v_readlane_b32 s54, v249, 56
	v_readlane_b32 s55, v249, 57
	v_lshl_add_u64 v[2:3], s[50:51], 0, v[0:1]
	s_add_u32 s24, s24, s21
	v_and_b32_e32 v64, 15, v132
	global_load_dword v119, v[2:3], off
	v_lshl_add_u64 v[2:3], s[54:55], 0, v[0:1]
	v_readlane_b32 s40, v250, 10
	s_addc_u32 s25, s25, 0
	v_and_b32_e32 v192, 48, v169
	v_readlane_b32 s42, v250, 12
	v_readlane_b32 s43, v250, 13
	v_readlane_b32 s44, v250, 14
	v_readlane_b32 s45, v250, 15
	v_lshl_add_u64 v[48:49], s[22:23], 0, v[192:193]
	v_lshl_add_u64 v[50:51], s[24:25], 0, v[192:193]
	v_lshlrev_b32_e32 v192, 7, v64
	global_load_dword v120, v[2:3], off
	v_lshl_add_u64 v[2:3], s[42:43], 0, v[0:1]
	v_lshl_add_u64 v[0:1], s[44:45], 0, v[0:1]
	s_waitcnt vmcnt(12)
	v_lshl_add_u64 v[20:21], v[48:49], 0, v[192:193]
	s_waitcnt vmcnt(10)
	v_lshl_add_u64 v[28:29], v[50:51], 0, v[192:193]
	global_load_dword v121, v[2:3], off
	global_load_dword v65, v[0:1], off
	s_nop 0
	global_load_dwordx4 v[0:3], v[20:21], off
	global_load_dwordx4 v[4:7], v[20:21], off offset:64
	global_load_dwordx4 v[8:11], v[28:29], off
	global_load_dwordx4 v[12:15], v[28:29], off offset:64
	global_load_dwordx4 v[16:19], v[20:21], off offset:2048
	s_nop 0
	global_load_dwordx4 v[20:23], v[20:21], off offset:2112
	s_nop 0
	global_load_dwordx4 v[24:27], v[28:29], off offset:2048
	s_nop 0
	global_load_dwordx4 v[28:31], v[28:29], off offset:2112
	v_or_b32_e32 v32, 0x1000, v192
	v_mov_b32_e32 v33, v193
	v_or_b32_e32 v192, 0x1800, v192
	v_lshl_add_u64 v[36:37], v[48:49], 0, v[32:33]
	v_lshl_add_u64 v[44:45], v[50:51], 0, v[32:33]
	v_lshl_add_u64 v[52:53], v[48:49], 0, v[192:193]
	v_lshl_add_u64 v[60:61], v[50:51], 0, v[192:193]
	global_load_dwordx4 v[32:35], v[36:37], off
	s_nop 0
	global_load_dwordx4 v[36:39], v[36:37], off offset:64
	s_nop 0
	global_load_dwordx4 v[40:43], v[44:45], off
	s_nop 0
	global_load_dwordx4 v[44:47], v[44:45], off offset:64
	s_nop 0
	global_load_dwordx4 v[48:51], v[52:53], off
	s_nop 0
	global_load_dwordx4 v[52:55], v[52:53], off offset:64
	s_nop 0
	global_load_dwordx4 v[56:59], v[60:61], off
	s_nop 0
	global_load_dwordx4 v[60:63], v[60:61], off offset:64
	s_mul_i32 s100, s57, 0x2600
	s_add_u32 s100, s100, s64
	s_addc_u32 s101, s65, 0
	s_add_u32 s100, s100, 0xbc01000
	s_addc_u32 s101, s101, 0
	v_lshlrev_b32_e32 v152, 1, v114
	v_mov_b32_e32 v153, 0
	v_lshl_add_u64 v[112:113], s[100:101], 0, v[152:153]
	v_lshrrev_b32_e32 v150, 6, v132
	v_lshlrev_b32_e32 v150, 4, v150
	s_lshl_b32 s100, s19, 8
	v_add_u32_e32 v150, s100, v150
	v_add_u32_e32 v151, -3, v150
	v_max_i32_e32 v151, 0, v151
	v_mad_u64_u32 v[152:153], vcc, v151, s33, v[112:113]
	global_load_ushort v209, v[152:153], off offset:512
	v_add_u32_e32 v151, -2, v150
	v_max_i32_e32 v151, 0, v151
	v_mad_u64_u32 v[152:153], vcc, v151, s33, v[112:113]
	global_load_ushort v210, v[152:153], off offset:512
	v_add_u32_e32 v151, -1, v150
	v_max_i32_e32 v151, 0, v151
	v_mad_u64_u32 v[152:153], vcc, v151, s33, v[112:113]
	global_load_ushort v211, v[152:153], off offset:512
	v_add_u32_e32 v151, 0, v150
	v_mad_u64_u32 v[152:153], vcc, v151, s33, v[112:113]
	global_load_ushort v212, v[152:153], off offset:512
	v_add_u32_e32 v151, 1, v150
	v_mad_u64_u32 v[152:153], vcc, v151, s33, v[112:113]
	global_load_ushort v213, v[152:153], off offset:512
	v_add_u32_e32 v151, 2, v150
	v_mad_u64_u32 v[152:153], vcc, v151, s33, v[112:113]
	global_load_ushort v214, v[152:153], off offset:512
	v_add_u32_e32 v151, 3, v150
	v_mad_u64_u32 v[152:153], vcc, v151, s33, v[112:113]
	global_load_ushort v215, v[152:153], off offset:512
	v_add_u32_e32 v151, 4, v150
	v_mad_u64_u32 v[152:153], vcc, v151, s33, v[112:113]
	global_load_ushort v216, v[152:153], off offset:512
	v_add_u32_e32 v151, 5, v150
	v_mad_u64_u32 v[152:153], vcc, v151, s33, v[112:113]
	global_load_ushort v217, v[152:153], off offset:512
	v_add_u32_e32 v151, 6, v150
	v_mad_u64_u32 v[152:153], vcc, v151, s33, v[112:113]
	global_load_ushort v218, v[152:153], off offset:512
	v_add_u32_e32 v151, 7, v150
	v_mad_u64_u32 v[152:153], vcc, v151, s33, v[112:113]
	global_load_ushort v219, v[152:153], off offset:512
	v_add_u32_e32 v151, 8, v150
	v_mad_u64_u32 v[152:153], vcc, v151, s33, v[112:113]
	global_load_ushort v220, v[152:153], off offset:512
	v_add_u32_e32 v151, 9, v150
	v_mad_u64_u32 v[152:153], vcc, v151, s33, v[112:113]
	global_load_ushort v221, v[152:153], off offset:512
	v_add_u32_e32 v151, 10, v150
	v_mad_u64_u32 v[152:153], vcc, v151, s33, v[112:113]
	global_load_ushort v222, v[152:153], off offset:512
	v_add_u32_e32 v151, 11, v150
	v_mad_u64_u32 v[152:153], vcc, v151, s33, v[112:113]
	global_load_ushort v223, v[152:153], off offset:512
	v_add_u32_e32 v151, 12, v150
	v_mad_u64_u32 v[152:153], vcc, v151, s33, v[112:113]
	global_load_ushort v224, v[152:153], off offset:512
	v_add_u32_e32 v151, 13, v150
	v_mad_u64_u32 v[152:153], vcc, v151, s33, v[112:113]
	global_load_ushort v225, v[152:153], off offset:512
	v_add_u32_e32 v151, 14, v150
	v_mad_u64_u32 v[152:153], vcc, v151, s33, v[112:113]
	global_load_ushort v226, v[152:153], off offset:512
	v_add_u32_e32 v151, 15, v150
	v_mad_u64_u32 v[152:153], vcc, v151, s33, v[112:113]
	global_load_ushort v227, v[152:153], off offset:512
	v_readlane_b32 s41, v250, 11
	v_cmp_gt_i32_e64 s[40:41], 64, v132
	v_readlane_b32 s46, v250, 16
	v_readlane_b32 s47, v250, 17
	v_readlane_b32 s48, v250, 18
	v_readlane_b32 s49, v250, 19
	v_readlane_b32 s50, v250, 20
	v_readlane_b32 s51, v250, 21
	v_readlane_b32 s52, v250, 22
	v_readlane_b32 s53, v250, 23
	v_readlane_b32 s54, v250, 24
	v_readlane_b32 s55, v250, 25
	s_and_saveexec_b64 s[42:43], s[40:41]
	s_cbranch_execz .LBB0_325
	v_lshl_add_u32 v66, v132, 2, 0
	v_add_u32_e32 v67, 0x15840, v66
	v_add_u32_e32 v66, 0x15940, v66
	ds_write_b32 v67, v193
	ds_write_b32 v66, v232
; __device__ __forceinline__ void lru_unit(const Ctx& C, const Params& p, int l, int unit) {
;     ...
;             unsigned* pf = flg + (size_t)(unit - 64) * 16;
;             while (__hip_atomic_load(pf, __ATOMIC_RELAXED, __HIP_MEMORY_SCOPE_AGENT) == 0u) __builtin_amdgcn_s_sleep(2);
;             cin = __hip_atomic_load(carr + (size_t)(unit - 64) * 64 + tid, __ATOMIC_RELAXED, __HIP_MEMORY_SCOPE_AGENT);
.LBB0_325:
	s_or_b64 exec, exec, s[42:43]
	s_waitcnt vmcnt(35)
	s_cmp_lg_u32 s72, 0
	s_cbranch_scc1 .Llru_pf2_skip
	s_cmp_lt_i32 s19, 1
	s_cbranch_scc1 .Llru_pf2_skip
	v_readfirstlane_b32 s100, v206
	v_mov_b32_e32 v206, 0
	s_cmp_lg_u32 s100, 0
	s_cbranch_scc0 .Llru_pf2_skip
	s_lshl_b32 s100, s19, 6
	s_or_b32 s100, s100, s20
	s_sub_i32 s100, s100, 64
	s_lshl_b32 s100, s100, 8
	v_lshl_add_u32 v208, v132, 2, s100
	v_readlane_b32 s100, v247, 17
	v_readlane_b32 s101, v247, 18
	s_nop 1
	s_add_u32 s100, s100, s64
	s_addc_u32 s101, s101, s65
	s_add_u32 s100, s100, 0x100000
	s_addc_u32 s101, s101, 0
	v_mov_b32_e32 v206, 1
	global_load_dword v207, v208, s[100:101] sc1

; __device__ __forceinline__ float bf2f(bf16 b) { return __uint_as_float((unsigned)b << 16); }
; __device__ __forceinline__ void lru_unit(const Ctx& C, const Params& p, int l, int unit) {
;     ...
;         const int tl0 = tile * 128 + 16 * tg, t0 = tc * 256 + tl0;
;         float xw[19], gbv[16], xc[16];
; #pragma unroll
;         for (int k = 0; k < 19; ++k) { const int t = t0 - 3 + k; xw[k] = (t >= 0) ? bf2f(Zb[(size_t)t * ZC + XB + ch]) : 0.f; }
.LBB0_327:
	v_add_u32_e32 v71, s24, v125
	v_add_u32_e32 v73, s21, v71
	v_lshlrev_b32_e32 v192, 1, v114
	v_mov_b64_e32 v[112:113], s[50:51]
	v_lshl_add_u64 v[112:113], v[112:113], 0, v[192:193]
	v_add_co_u32_e32 v112, vcc, 0x1000, v112
	v_add_u32_e32 v65, -3, v73
	v_add_u32_e32 v64, -2, v73
	v_addc_co_u32_e32 v113, vcc, 0, v113, vcc
	v_add_u32_e32 v67, -1, v73
	v_max_i32_e32 v65, 0, v65
	v_max_i32_e32 v64, 0, v64
	v_max_i32_e32 v67, 0, v67
	v_or_b32_e32 v74, 1, v73
	v_or_b32_e32 v79, 2, v73
	v_or_b32_e32 v80, 3, v73
	v_or_b32_e32 v81, 4, v73
	v_or_b32_e32 v84, 5, v73
	v_or_b32_e32 v86, 6, v73
	v_or_b32_e32 v92, 7, v73
	v_or_b32_e32 v87, 8, v73
	v_or_b32_e32 v93, 9, v73
	v_or_b32_e32 v98, 10, v73
	v_or_b32_e32 v99, 11, v73
	v_or_b32_e32 v104, 12, v73
	v_or_b32_e32 v105, 13, v73
	v_or_b32_e32 v108, 14, v73
	v_or_b32_e32 v110, 15, v73
	s_waitcnt vmcnt(0)
	v_mov_b32_e32 v65, v209
	v_mov_b32_e32 v64, v210
	v_mov_b32_e32 v67, v211
	v_mov_b32_e32 v66, v212
	v_mov_b32_e32 v69, v213
	v_mov_b32_e32 v68, v214
	v_mov_b32_e32 v72, v215
	v_mov_b32_e32 v70, v216
	v_mov_b32_e32 v76, v217
	v_mov_b32_e32 v75, v218
	v_mov_b32_e32 v82, v219
	v_mov_b32_e32 v78, v220
	v_mov_b32_e32 v90, v221
	v_mov_b32_e32 v88, v222
	v_mov_b32_e32 v96, v223
	v_mov_b32_e32 v94, v224
	v_mov_b32_e32 v102, v225
	v_mov_b32_e32 v100, v226
	v_mov_b32_e32 v106, v227
	s_cmp_lg_u32 s24, 0
	s_cbranch_scc1 .Llru_conv
	v_add_u32_e32 v153, 125, v73
	v_mad_u64_u32 v[150:151], s[22:23], v153, s33, v[112:113]
	global_load_ushort v209, v[150:151], off offset:512
	v_add_u32_e32 v153, 126, v73
	v_mad_u64_u32 v[150:151], s[22:23], v153, s33, v[112:113]
	global_load_ushort v210, v[150:151], off offset:512
	v_add_u32_e32 v153, 127, v73
	v_mad_u64_u32 v[150:151], s[22:23], v153, s33, v[112:113]
	global_load_ushort v211, v[150:151], off offset:512
	v_add_u32_e32 v153, 128, v73
	v_mad_u64_u32 v[150:151], s[22:23], v153, s33, v[112:113]
	global_load_ushort v212, v[150:151], off offset:512
	v_add_u32_e32 v153, 129, v73
	v_mad_u64_u32 v[150:151], s[22:23], v153, s33, v[112:113]
	global_load_ushort v213, v[150:151], off offset:512
	v_add_u32_e32 v153, 130, v73
	v_mad_u64_u32 v[150:151], s[22:23], v153, s33, v[112:113]
	global_load_ushort v214, v[150:151], off offset:512
	v_add_u32_e32 v153, 131, v73
	v_mad_u64_u32 v[150:151], s[22:23], v153, s33, v[112:113]
	global_load_ushort v215, v[150:151], off offset:512
	v_add_u32_e32 v153, 132, v73
	v_mad_u64_u32 v[150:151], s[22:23], v153, s33, v[112:113]
	global_load_ushort v216, v[150:151], off offset:512
	v_add_u32_e32 v153, 133, v73
	v_mad_u64_u32 v[150:151], s[22:23], v153, s33, v[112:113]
	global_load_ushort v217, v[150:151], off offset:512
	v_add_u32_e32 v153, 134, v73
	v_mad_u64_u32 v[150:151], s[22:23], v153, s33, v[112:113]
	global_load_ushort v218, v[150:151], off offset:512
	v_add_u32_e32 v153, 135, v73
	v_mad_u64_u32 v[150:151], s[22:23], v153, s33, v[112:113]
	global_load_ushort v219, v[150:151], off offset:512
	v_add_u32_e32 v153, 136, v73
	v_mad_u64_u32 v[150:151], s[22:23], v153, s33, v[112:113]
	global_load_ushort v220, v[150:151], off offset:512
	v_add_u32_e32 v153, 137, v73
	v_mad_u64_u32 v[150:151], s[22:23], v153, s33, v[112:113]
	global_load_ushort v221, v[150:151], off offset:512
	v_add_u32_e32 v153, 138, v73
	v_mad_u64_u32 v[150:151], s[22:23], v153, s33, v[112:113]
	global_load_ushort v222, v[150:151], off offset:512
	v_add_u32_e32 v153, 139, v73
	v_mad_u64_u32 v[150:151], s[22:23], v153, s33, v[112:113]
	global_load_ushort v223, v[150:151], off offset:512
	v_add_u32_e32 v153, 140, v73
	v_mad_u64_u32 v[150:151], s[22:23], v153, s33, v[112:113]
	global_load_ushort v224, v[150:151], off offset:512
	v_add_u32_e32 v153, 141, v73
	v_mad_u64_u32 v[150:151], s[22:23], v153, s33, v[112:113]
	global_load_ushort v225, v[150:151], off offset:512
	v_add_u32_e32 v153, 142, v73
	v_mad_u64_u32 v[150:151], s[22:23], v153, s33, v[112:113]
	global_load_ushort v226, v[150:151], off offset:512
	v_add_u32_e32 v153, 143, v73
	v_mad_u64_u32 v[150:151], s[22:23], v153, s33, v[112:113]
	global_load_ushort v227, v[150:151], off offset:512
